# grid barrier: non-leader blocks poll the top generation word directly instead of the per-XCD generation (one hop less)
# speedup vs baseline: 1.0242x; 1.0018x over previous
; __device__ __forceinline__ unsigned xb_ld(unsigned* p)              { return __hip_atomic_load(p, __ATOMIC_RELAXED, __HIP_MEMORY_SCOPE_AGENT); }
; __device__ __forceinline__ unsigned xb_add(unsigned* p, unsigned v) { return __hip_atomic_fetch_add(p, v, __ATOMIC_RELAXED, __HIP_MEMORY_SCOPE_AGENT); }
; #define XB_SPIN(cond, bar) do { unsigned _sp = 0; while (cond) { __builtin_amdgcn_s_sleep(1); \
;     if ((++_sp & 255u) == 0u) { if (xb_ld(&(bar)[XB_TMO])) break; if (_sp > XB_SPIN_CAP) { atomicAdd(&(bar)[XB_TMO], 1u); break; } } } } while (0)
; __device__ __forceinline__ void xcd_barrier(const XcdBarrier& b) {
;     ...
;         const unsigned old = xb_add(&bar[XB_XSUB(bx)], 1u);
;         const unsigned gen = old / nloc;
;         if (old + 1u == (gen + 1u) * nloc) {
;             __builtin_amdgcn_fence(__ATOMIC_RELEASE, "agent");
;             asm volatile("s_waitcnt vmcnt(0)" ::: "memory");
;             const unsigned og = xb_add(&bar[XB_TOP], 1u);
;             const unsigned tg = og / nx;
;             if (og + 1u == (tg + 1u) * nx) xb_add(&bar[XB_TOPGEN], 1u);
;             else XB_SPIN(xb_ld(&bar[XB_TOPGEN]) == tg, bar);
;             __builtin_amdgcn_fence(__ATOMIC_ACQUIRE, "agent");
;             xb_add(&bar[XB_XGEN(bx)], 1u);
;             asm volatile("s_waitcnt vmcnt(0)" ::: "memory");
;         } else {
;             XB_SPIN(xb_ld(&bar[XB_XGEN(bx)]) == gen, bar);
.LBB0_608:
	s_or_b64 exec, exec, s[4:5]
	v_cvt_f32_u32_e32 v6, v4
	s_waitcnt vmcnt(0)
	v_readfirstlane_b32 s2, v5
	v_sub_u32_e32 v5, 0, v4
	v_rcp_iflag_f32_e32 v6, v6
	v_add_u32_e32 v7, s2, v3
	v_mul_f32_e32 v6, 0x4f7ffffe, v6
	v_cvt_u32_f32_e32 v6, v6
	v_mul_lo_u32 v3, v5, v6
	v_mul_hi_u32 v3, v6, v3
	v_add_u32_e32 v3, v6, v3
	v_mul_hi_u32 v3, v7, v3
	v_mul_lo_u32 v5, v3, v4
	v_sub_u32_e32 v5, v7, v5
	v_add_u32_e32 v6, 1, v3
	v_cmp_ge_u32_e32 vcc, v5, v4
	s_nop 1
	v_cndmask_b32_e32 v3, v3, v6, vcc
	v_sub_u32_e32 v6, v5, v4
	v_cndmask_b32_e32 v5, v5, v6, vcc
	v_add_u32_e32 v6, 1, v3
	v_cmp_ge_u32_e32 vcc, v5, v4
	v_add_u32_e32 v5, 1, v7
	s_nop 0
	v_cndmask_b32_e32 v3, v3, v6, vcc
	v_mul_lo_u32 v6, v4, v3
	v_add_u32_e32 v4, v6, v4
	v_cmp_ne_u32_e32 vcc, v5, v4
	s_and_saveexec_b64 s[2:3], vcc
	s_xor_b64 s[2:3], exec, s[2:3]
	s_cbranch_execz .LBB0_622
	s_movk_i32 s4, 0xd40
	s_mov_b32 s5, 0
	s_lshl_b64 s[4:5], s[4:5], 2
	s_add_u32 s6, s78, s4
	s_addc_u32 s7, s79, s5
	s_waitcnt lgkmcnt(0)
	v_mov_b32_e32 v2, 0
	global_load_dword v4, v2, s[6:7] sc1
	s_waitcnt vmcnt(0)
	v_cmp_eq_u32_e32 vcc, v4, v3
	s_and_saveexec_b64 s[4:5], vcc
	s_cbranch_execz .LBB0_621
	s_mov_b32 s18, 1
	s_mov_b64 s[8:9], 0
	s_branch .LBB0_612

; __device__ __forceinline__ unsigned xb_ld(unsigned* p)              { return __hip_atomic_load(p, __ATOMIC_RELAXED, __HIP_MEMORY_SCOPE_AGENT); }
; __device__ __forceinline__ unsigned xb_add(unsigned* p, unsigned v) { return __hip_atomic_fetch_add(p, v, __ATOMIC_RELAXED, __HIP_MEMORY_SCOPE_AGENT); }
; #define XB_SPIN(cond, bar) do { unsigned _sp = 0; while (cond) { __builtin_amdgcn_s_sleep(1); \
;     if ((++_sp & 255u) == 0u) { if (xb_ld(&(bar)[XB_TMO])) break; if (_sp > XB_SPIN_CAP) { atomicAdd(&(bar)[XB_TMO], 1u); break; } } } } while (0)
; __device__ __forceinline__ void xcd_barrier(const XcdBarrier& b) {
;     ...
;         const unsigned old = xb_add(&bar[XB_XSUB(bx)], 1u);
;         const unsigned gen = old / nloc;
;         if (old + 1u == (gen + 1u) * nloc) {
;             __builtin_amdgcn_fence(__ATOMIC_RELEASE, "agent");
;             asm volatile("s_waitcnt vmcnt(0)" ::: "memory");
;             const unsigned og = xb_add(&bar[XB_TOP], 1u);
;             const unsigned tg = og / nx;
;             if (og + 1u == (tg + 1u) * nx) xb_add(&bar[XB_TOPGEN], 1u);
;             else XB_SPIN(xb_ld(&bar[XB_TOPGEN]) == tg, bar);
;             __builtin_amdgcn_fence(__ATOMIC_ACQUIRE, "agent");
;             xb_add(&bar[XB_XGEN(bx)], 1u);
;             asm volatile("s_waitcnt vmcnt(0)" ::: "memory");
;         } else {
;             XB_SPIN(xb_ld(&bar[XB_XGEN(bx)]) == gen, bar);
.LBB0_788:
	s_or_b64 exec, exec, s[6:7]
	v_cvt_f32_u32_e32 v6, v4
	s_waitcnt vmcnt(0)
	v_readfirstlane_b32 s4, v5
	v_sub_u32_e32 v5, 0, v4
	v_rcp_iflag_f32_e32 v6, v6
	v_add_u32_e32 v7, s4, v3
	v_mul_f32_e32 v6, 0x4f7ffffe, v6
	v_cvt_u32_f32_e32 v6, v6
	v_mul_lo_u32 v3, v5, v6
	v_mul_hi_u32 v3, v6, v3
	v_add_u32_e32 v3, v6, v3
	v_mul_hi_u32 v3, v7, v3
	v_mul_lo_u32 v5, v3, v4
	v_sub_u32_e32 v5, v7, v5
	v_add_u32_e32 v6, 1, v3
	v_cmp_ge_u32_e32 vcc, v5, v4
	s_nop 1
	v_cndmask_b32_e32 v3, v3, v6, vcc
	v_sub_u32_e32 v6, v5, v4
	v_cndmask_b32_e32 v5, v5, v6, vcc
	v_add_u32_e32 v6, 1, v3
	v_cmp_ge_u32_e32 vcc, v5, v4
	v_add_u32_e32 v5, 1, v7
	s_nop 0
	v_cndmask_b32_e32 v3, v3, v6, vcc
	v_mul_lo_u32 v6, v4, v3
	v_add_u32_e32 v4, v6, v4
	v_cmp_ne_u32_e32 vcc, v5, v4
	s_and_saveexec_b64 s[4:5], vcc
	s_xor_b64 s[4:5], exec, s[4:5]
	s_cbranch_execz .LBB0_802
	s_movk_i32 s82, 0xd40
	s_lshl_b64 s[6:7], s[82:83], 2
	s_add_u32 s8, s78, s6
	s_addc_u32 s9, s79, s7
	s_waitcnt lgkmcnt(0)
	global_load_dword v2, v169, s[8:9] sc1
	s_waitcnt vmcnt(0)
	v_cmp_eq_u32_e32 vcc, v2, v3
	s_and_saveexec_b64 s[6:7], vcc
	s_cbranch_execz .LBB0_801
	s_mov_b32 s21, 1
	s_mov_b64 s[10:11], 0
	s_branch .LBB0_792

; __device__ __forceinline__ unsigned xb_ld(unsigned* p)              { return __hip_atomic_load(p, __ATOMIC_RELAXED, __HIP_MEMORY_SCOPE_AGENT); }
; __device__ __forceinline__ unsigned xb_add(unsigned* p, unsigned v) { return __hip_atomic_fetch_add(p, v, __ATOMIC_RELAXED, __HIP_MEMORY_SCOPE_AGENT); }
; #define XB_SPIN(cond, bar) do { unsigned _sp = 0; while (cond) { __builtin_amdgcn_s_sleep(1); \
;     if ((++_sp & 255u) == 0u) { if (xb_ld(&(bar)[XB_TMO])) break; if (_sp > XB_SPIN_CAP) { atomicAdd(&(bar)[XB_TMO], 1u); break; } } } } while (0)
; __device__ __forceinline__ void xcd_barrier(const XcdBarrier& b) {
;     ...
;         const unsigned old = xb_add(&bar[XB_XSUB(bx)], 1u);
;         const unsigned gen = old / nloc;
;         if (old + 1u == (gen + 1u) * nloc) {
;             __builtin_amdgcn_fence(__ATOMIC_RELEASE, "agent");
;             asm volatile("s_waitcnt vmcnt(0)" ::: "memory");
;             const unsigned og = xb_add(&bar[XB_TOP], 1u);
;             const unsigned tg = og / nx;
;             if (og + 1u == (tg + 1u) * nx) xb_add(&bar[XB_TOPGEN], 1u);
;             else XB_SPIN(xb_ld(&bar[XB_TOPGEN]) == tg, bar);
;             __builtin_amdgcn_fence(__ATOMIC_ACQUIRE, "agent");
;             xb_add(&bar[XB_XGEN(bx)], 1u);
;             asm volatile("s_waitcnt vmcnt(0)" ::: "memory");
;         } else {
;             XB_SPIN(xb_ld(&bar[XB_XGEN(bx)]) == gen, bar);
.LBB0_2331:
	s_or_b64 exec, exec, s[6:7]
	v_cvt_f32_u32_e32 v6, v4
	s_waitcnt vmcnt(0)
	v_readfirstlane_b32 s4, v5
	v_sub_u32_e32 v5, 0, v4
	v_rcp_iflag_f32_e32 v6, v6
	v_add_u32_e32 v7, s4, v3
	v_mul_f32_e32 v6, 0x4f7ffffe, v6
	v_cvt_u32_f32_e32 v6, v6
	v_mul_lo_u32 v3, v5, v6
	v_mul_hi_u32 v3, v6, v3
	v_add_u32_e32 v3, v6, v3
	v_mul_hi_u32 v3, v7, v3
	v_mul_lo_u32 v5, v3, v4
	v_sub_u32_e32 v5, v7, v5
	v_add_u32_e32 v6, 1, v3
	v_cmp_ge_u32_e32 vcc, v5, v4
	s_nop 1
	v_cndmask_b32_e32 v3, v3, v6, vcc
	v_sub_u32_e32 v6, v5, v4
	v_cndmask_b32_e32 v5, v5, v6, vcc
	v_add_u32_e32 v6, 1, v3
	v_cmp_ge_u32_e32 vcc, v5, v4
	v_add_u32_e32 v5, 1, v7
	s_nop 0
	v_cndmask_b32_e32 v3, v3, v6, vcc
	v_mul_lo_u32 v6, v4, v3
	v_add_u32_e32 v4, v6, v4
	v_cmp_ne_u32_e32 vcc, v5, v4
	s_and_saveexec_b64 s[4:5], vcc
	s_xor_b64 s[4:5], exec, s[4:5]
	s_cbranch_execz .LBB0_2345
	s_movk_i32 s82, 0xd40
	s_lshl_b64 s[6:7], s[82:83], 2
	s_add_u32 s8, s78, s6
	s_addc_u32 s9, s79, s7
	s_waitcnt lgkmcnt(0)
	global_load_dword v2, v169, s[8:9] sc1
	s_waitcnt vmcnt(0)
	v_cmp_eq_u32_e32 vcc, v2, v3
	s_and_saveexec_b64 s[6:7], vcc
	s_cbranch_execz .LBB0_2344
	s_mov_b32 s23, 1
	s_mov_b64 s[10:11], 0
	s_branch .LBB0_2335
